# panel syncs (same-XCD case): early L1 invalidate + pipelined counter polls (4 in flight), no post-wait invalidate
# speedup vs baseline: 1.0021x; 1.0021x over previous
.LBB0_419:
	s_or_b64 exec, exec, s[8:9]
	v_mov_b32_e32 v0, 0
	v_readlane_b32 s98, v251, 24
	s_cmp_lg_u32 s98, 0
	s_cbranch_scc1 .Lfp_orig_0
	buffer_inv sc1
	v_mov_b32_e32 v252, 0
	s_mov_b32 s98, 0
.Lfp_loop_0:
	global_load_dword v252, v0, s[4:5] sc1
	s_add_i32 s98, s98, 1
	s_waitcnt vmcnt(3)
	v_readfirstlane_b32 s99, v252
	s_cmp_gt_u32 s99, 3
	s_cbranch_scc1 .LBB0_433
	s_cmp_lt_u32 s98, 0x100000
	s_cbranch_scc1 .Lfp_loop_0
	s_branch .LBB0_433

.LBB0_461:
	s_or_b64 exec, exec, s[12:13]
	v_mov_b32_e32 v0, 0
	v_readlane_b32 s98, v251, 24
	s_cmp_lg_u32 s98, 0
	s_cbranch_scc1 .Lfp_orig_1
	buffer_inv sc1
	v_mov_b32_e32 v252, 0
	s_mov_b32 s98, 0
.Lfp_loop_1:
	global_load_dword v252, v0, s[8:9] sc1
	s_add_i32 s98, s98, 1
	s_waitcnt vmcnt(3)
	v_readfirstlane_b32 s99, v252
	s_cmp_gt_u32 s99, 3
	s_cbranch_scc1 .LBB0_475
	s_cmp_lt_u32 s98, 0x100000
	s_cbranch_scc1 .Lfp_loop_1
	s_branch .LBB0_475
